# v68 + GEMM main loops: half of the LDS-DMAs use the SGPR-base + 32-bit VGPR offset form (no 64-bit VALU add in front of the DMA)
# baseline (speedup 1.0000x reference)
.LBB0_143:
	ds_read_b128 v[96:99], v183
	ds_read_b128 v[100:103], v183 offset:1024
	ds_read_b128 v[112:115], v183 offset:2048
	ds_read_b128 v[120:123], v183 offset:3072
	ds_read_b128 v[144:147], v184
	ds_read_b128 v[170:173], v184 offset:1024
	ds_read_b128 v[186:189], v184 offset:2048
	ds_read_b128 v[190:193], v184 offset:3072
	s_add_u32 s44, s0, 0xfffc0080
	s_addc_u32 s45, s1, -1
	s_cmp_eq_u32 s89, 12
	s_cselect_b32 s87, s77, s45
	s_cselect_b32 s86, vcc_lo, s44
	s_cselect_b32 s85, s75, s15
	s_cselect_b32 s84, vcc_hi, s14
	s_nop 0
	s_add_i32 m0, s92, 0xc000
	ds_read_b128 v[198:201], v185
	ds_read_b128 v[206:209], v185 offset:1024
	ds_read_b128 v[210:213], v185 offset:2048
	ds_read_b128 v[214:217], v185 offset:3072
	ds_read_b128 v[218:221], v185 offset:4096
	ds_read_b128 v[222:225], v185 offset:5120
	ds_read_b128 v[226:229], v185 offset:6144
	ds_read_b128 v[230:233], v185 offset:7168
	global_load_lds_dwordx4 v162, s[0:1]
	s_nop 0
	s_add_i32 m0, s92, 0xe000
	s_nop 0
	global_load_lds_dwordx4 v164, s[0:1]
	s_waitcnt vmcnt(8)
	s_waitcnt lgkmcnt(0)
	s_barrier
	s_setprio 1
	s_waitcnt lgkmcnt(0)
	v_mfma_f32_16x16x32_bf16 v[140:143], v[96:99], v[198:201], v[140:143]
	v_mfma_f32_16x16x32_bf16 v[136:139], v[112:115], v[198:201], v[136:139]
	v_mfma_f32_16x16x32_bf16 v[124:127], v[96:99], v[210:213], v[124:127]
	v_mfma_f32_16x16x32_bf16 v[116:119], v[112:115], v[210:213], v[116:119]
	v_mfma_f32_16x16x32_bf16 v[92:95], v[96:99], v[218:221], v[92:95]
	v_mfma_f32_16x16x32_bf16 v[88:91], v[112:115], v[218:221], v[88:91]
	v_mfma_f32_16x16x32_bf16 v[76:79], v[96:99], v[226:229], v[76:79]
	v_mfma_f32_16x16x32_bf16 v[72:75], v[112:115], v[226:229], v[72:75]
	v_mfma_f32_16x16x32_bf16 v[140:143], v[100:103], v[206:209], v[140:143]
	v_mfma_f32_16x16x32_bf16 v[136:139], v[120:123], v[206:209], v[136:139]
	v_mfma_f32_16x16x32_bf16 v[124:127], v[100:103], v[214:217], v[124:127]
	v_mfma_f32_16x16x32_bf16 v[116:119], v[120:123], v[214:217], v[116:119]
	v_mfma_f32_16x16x32_bf16 v[92:95], v[100:103], v[222:225], v[92:95]
	v_mfma_f32_16x16x32_bf16 v[88:91], v[120:123], v[222:225], v[88:91]
	v_mfma_f32_16x16x32_bf16 v[76:79], v[100:103], v[230:233], v[76:79]
	v_mfma_f32_16x16x32_bf16 v[72:75], v[120:123], v[230:233], v[72:75]
	s_setprio 0
	s_setprio 1
	v_mfma_f32_16x16x32_bf16 v[128:131], v[144:147], v[198:201], v[128:131]
	v_mfma_f32_16x16x32_bf16 v[132:135], v[186:189], v[198:201], v[132:135]
	v_mfma_f32_16x16x32_bf16 v[104:107], v[144:147], v[210:213], v[104:107]
	v_mfma_f32_16x16x32_bf16 v[108:111], v[186:189], v[210:213], v[108:111]
	v_mfma_f32_16x16x32_bf16 v[80:83], v[144:147], v[218:221], v[80:83]
	v_mfma_f32_16x16x32_bf16 v[84:87], v[186:189], v[218:221], v[84:87]
	v_mfma_f32_16x16x32_bf16 v[64:67], v[144:147], v[226:229], v[64:67]
	v_mfma_f32_16x16x32_bf16 v[68:71], v[186:189], v[226:229], v[68:71]
	v_mfma_f32_16x16x32_bf16 v[128:131], v[170:173], v[206:209], v[128:131]
	v_mfma_f32_16x16x32_bf16 v[132:135], v[190:193], v[206:209], v[132:135]
	v_mfma_f32_16x16x32_bf16 v[104:107], v[170:173], v[214:217], v[104:107]
	v_mfma_f32_16x16x32_bf16 v[108:111], v[190:193], v[214:217], v[108:111]
	v_mfma_f32_16x16x32_bf16 v[80:83], v[170:173], v[222:225], v[80:83]
	v_mfma_f32_16x16x32_bf16 v[84:87], v[190:193], v[222:225], v[84:87]
	v_mfma_f32_16x16x32_bf16 v[64:67], v[170:173], v[230:233], v[64:67]
	v_mfma_f32_16x16x32_bf16 v[68:71], v[190:193], v[230:233], v[68:71]
	s_setprio 0
	s_barrier
	s_add_i32 s44, s56, s91
	v_lshl_add_u64 v[194:195], s[84:85], 0, v[150:151]
	s_mov_b32 m0, s44
	ds_read_b128 v[198:201], v185 offset:16384
	ds_read_b128 v[206:209], v185 offset:17408
	ds_read_b128 v[210:213], v185 offset:18432
	ds_read_b128 v[214:217], v185 offset:19456
	ds_read_b128 v[218:221], v185 offset:20480
	ds_read_b128 v[222:225], v185 offset:21504
	ds_read_b128 v[226:229], v185 offset:22528
	ds_read_b128 v[230:233], v185 offset:23552
	global_load_lds_dwordx4 v[194:195], off
	s_add_i32 m0, s44, 0x2000
	s_add_u32 s44, s84, 0x40000
	v_lshl_add_u64 v[234:235], s[84:85], 0, v[154:155]
	s_addc_u32 s45, s85, 0
	s_add_i32 s90, s57, s91
	global_load_lds_dwordx4 v[234:235], off
	s_nop 0
	s_mov_b32 m0, s90
	v_lshl_add_u64 v[238:239], s[86:87], 0, v[152:153]
	global_load_lds_dwordx4 v150, s[44:45]
	s_nop 0
	s_add_i32 m0, s90, 0x2000
	s_nop 0
	global_load_lds_dwordx4 v154, s[44:45]
	v_lshl_add_u64 v[236:237], s[86:87], 0, v[148:149]
	s_mov_b32 m0, s92
	s_nop 0
	global_load_lds_dwordx4 v[236:237], off
	s_mov_b32 m0, s93
	s_nop 0
	global_load_lds_dwordx4 v[238:239], off
	s_waitcnt vmcnt(8)
	s_waitcnt lgkmcnt(0)
	s_barrier
	s_setprio 1
	s_waitcnt lgkmcnt(0)
	v_mfma_f32_16x16x32_bf16 v[60:63], v[96:99], v[198:201], v[60:63]
	v_mfma_f32_16x16x32_bf16 v[56:59], v[112:115], v[198:201], v[56:59]
	v_mfma_f32_16x16x32_bf16 v[44:47], v[96:99], v[210:213], v[44:47]
	v_mfma_f32_16x16x32_bf16 v[40:43], v[112:115], v[210:213], v[40:43]
	v_mfma_f32_16x16x32_bf16 v[28:31], v[96:99], v[218:221], v[28:31]
	v_mfma_f32_16x16x32_bf16 v[24:27], v[112:115], v[218:221], v[24:27]
	v_mfma_f32_16x16x32_bf16 v[12:15], v[96:99], v[226:229], v[12:15]
	v_mfma_f32_16x16x32_bf16 v[8:11], v[112:115], v[226:229], v[8:11]
	v_mfma_f32_16x16x32_bf16 v[60:63], v[100:103], v[206:209], v[60:63]
	v_mfma_f32_16x16x32_bf16 v[56:59], v[120:123], v[206:209], v[56:59]
	v_mfma_f32_16x16x32_bf16 v[44:47], v[100:103], v[214:217], v[44:47]
	v_mfma_f32_16x16x32_bf16 v[40:43], v[120:123], v[214:217], v[40:43]
	v_mfma_f32_16x16x32_bf16 v[28:31], v[100:103], v[222:225], v[28:31]
	v_mfma_f32_16x16x32_bf16 v[24:27], v[120:123], v[222:225], v[24:27]
	v_mfma_f32_16x16x32_bf16 v[12:15], v[100:103], v[230:233], v[12:15]
	v_mfma_f32_16x16x32_bf16 v[8:11], v[120:123], v[230:233], v[8:11]
	s_setprio 0
	s_setprio 1
	v_mfma_f32_16x16x32_bf16 v[48:51], v[144:147], v[198:201], v[48:51]
	v_mfma_f32_16x16x32_bf16 v[52:55], v[186:189], v[198:201], v[52:55]
	v_mfma_f32_16x16x32_bf16 v[32:35], v[144:147], v[210:213], v[32:35]
	v_mfma_f32_16x16x32_bf16 v[36:39], v[186:189], v[210:213], v[36:39]
	v_mfma_f32_16x16x32_bf16 v[16:19], v[144:147], v[218:221], v[16:19]
	v_mfma_f32_16x16x32_bf16 v[20:23], v[186:189], v[218:221], v[20:23]
	v_mfma_f32_16x16x32_bf16 v[4:7], v[144:147], v[226:229], v[4:7]
	v_mfma_f32_16x16x32_bf16 v[0:3], v[186:189], v[226:229], v[0:3]
	v_mfma_f32_16x16x32_bf16 v[48:51], v[170:173], v[206:209], v[48:51]
	v_mfma_f32_16x16x32_bf16 v[52:55], v[190:193], v[206:209], v[52:55]
	v_mfma_f32_16x16x32_bf16 v[32:35], v[170:173], v[214:217], v[32:35]
	v_mfma_f32_16x16x32_bf16 v[36:39], v[190:193], v[214:217], v[36:39]
	v_mfma_f32_16x16x32_bf16 v[16:19], v[170:173], v[222:225], v[16:19]
	v_mfma_f32_16x16x32_bf16 v[20:23], v[190:193], v[222:225], v[20:23]
	v_mfma_f32_16x16x32_bf16 v[4:7], v[170:173], v[230:233], v[4:7]
	v_mfma_f32_16x16x32_bf16 v[0:3], v[190:193], v[230:233], v[0:3]
	s_setprio 0
	s_barrier
	s_add_i32 s90, 0, 0x18000
	s_add_i32 s33, 0, 0x1c000
	v_add_u32_e32 v120, s90, v175
	v_add_u32_e32 v190, s33, v175
	ds_read_b128 v[96:99], v120
	ds_read_b128 v[100:103], v120 offset:1024
	ds_read_b128 v[112:115], v120 offset:2048
	ds_read_b128 v[120:123], v120 offset:3072
	ds_read_b128 v[144:147], v190
	ds_read_b128 v[170:173], v190 offset:1024
	ds_read_b128 v[186:189], v190 offset:2048
	ds_read_b128 v[190:193], v190 offset:3072
	s_add_u32 s44, s86, 0x40000
	s_addc_u32 s45, s87, 0
	s_mov_b32 m0, s94
	s_nop 0
	ds_read_b128 v[198:201], v185 offset:32768
	ds_read_b128 v[206:209], v185 offset:33792
	ds_read_b128 v[210:213], v185 offset:34816
	ds_read_b128 v[214:217], v185 offset:35840
	ds_read_b128 v[218:221], v185 offset:36864
	ds_read_b128 v[222:225], v185 offset:37888
	ds_read_b128 v[226:229], v185 offset:38912
	ds_read_b128 v[230:233], v185 offset:39936
	global_load_lds_dwordx4 v148, s[44:45]
	s_nop 0
	s_mov_b32 m0, s95
	s_nop 0
	global_load_lds_dwordx4 v152, s[44:45]
	s_waitcnt vmcnt(8)
	s_waitcnt lgkmcnt(0)
	s_barrier
	s_setprio 1
	s_waitcnt lgkmcnt(0)
	v_mfma_f32_16x16x32_bf16 v[140:143], v[96:99], v[198:201], v[140:143]
	v_mfma_f32_16x16x32_bf16 v[136:139], v[112:115], v[198:201], v[136:139]
	v_mfma_f32_16x16x32_bf16 v[124:127], v[96:99], v[210:213], v[124:127]
	v_mfma_f32_16x16x32_bf16 v[116:119], v[112:115], v[210:213], v[116:119]
	v_mfma_f32_16x16x32_bf16 v[92:95], v[96:99], v[218:221], v[92:95]
	v_mfma_f32_16x16x32_bf16 v[88:91], v[112:115], v[218:221], v[88:91]
	v_mfma_f32_16x16x32_bf16 v[76:79], v[96:99], v[226:229], v[76:79]
	v_mfma_f32_16x16x32_bf16 v[72:75], v[112:115], v[226:229], v[72:75]
	v_mfma_f32_16x16x32_bf16 v[140:143], v[100:103], v[206:209], v[140:143]
	v_mfma_f32_16x16x32_bf16 v[136:139], v[120:123], v[206:209], v[136:139]
	v_mfma_f32_16x16x32_bf16 v[124:127], v[100:103], v[214:217], v[124:127]
	v_mfma_f32_16x16x32_bf16 v[116:119], v[120:123], v[214:217], v[116:119]
	v_mfma_f32_16x16x32_bf16 v[92:95], v[100:103], v[222:225], v[92:95]
	v_mfma_f32_16x16x32_bf16 v[88:91], v[120:123], v[222:225], v[88:91]
	v_mfma_f32_16x16x32_bf16 v[76:79], v[100:103], v[230:233], v[76:79]
	v_mfma_f32_16x16x32_bf16 v[72:75], v[120:123], v[230:233], v[72:75]
	s_setprio 0
	s_setprio 1
	v_mfma_f32_16x16x32_bf16 v[128:131], v[144:147], v[198:201], v[128:131]
	v_mfma_f32_16x16x32_bf16 v[132:135], v[186:189], v[198:201], v[132:135]
	v_mfma_f32_16x16x32_bf16 v[104:107], v[144:147], v[210:213], v[104:107]
	v_mfma_f32_16x16x32_bf16 v[108:111], v[186:189], v[210:213], v[108:111]
	v_mfma_f32_16x16x32_bf16 v[80:83], v[144:147], v[218:221], v[80:83]
	v_mfma_f32_16x16x32_bf16 v[84:87], v[186:189], v[218:221], v[84:87]
	v_mfma_f32_16x16x32_bf16 v[64:67], v[144:147], v[226:229], v[64:67]
	v_mfma_f32_16x16x32_bf16 v[68:71], v[186:189], v[226:229], v[68:71]
	v_mfma_f32_16x16x32_bf16 v[128:131], v[170:173], v[206:209], v[128:131]
	v_mfma_f32_16x16x32_bf16 v[132:135], v[190:193], v[206:209], v[132:135]
	v_mfma_f32_16x16x32_bf16 v[104:107], v[170:173], v[214:217], v[104:107]
	v_mfma_f32_16x16x32_bf16 v[108:111], v[190:193], v[214:217], v[108:111]
	v_mfma_f32_16x16x32_bf16 v[80:83], v[170:173], v[222:225], v[80:83]
	v_mfma_f32_16x16x32_bf16 v[84:87], v[190:193], v[222:225], v[84:87]
	v_mfma_f32_16x16x32_bf16 v[64:67], v[170:173], v[230:233], v[64:67]
	v_mfma_f32_16x16x32_bf16 v[68:71], v[190:193], v[230:233], v[68:71]
	s_setprio 0
	s_barrier
	s_add_i32 s44, s90, s91
	v_lshl_add_u64 v[194:195], v[194:195], 0, s[62:63]
	s_mov_b32 m0, s44
	ds_read_b128 v[198:201], v185 offset:49152
	ds_read_b128 v[206:209], v185 offset:50176
	ds_read_b128 v[210:213], v185 offset:51200
	ds_read_b128 v[214:217], v185 offset:52224
	ds_read_b128 v[218:221], v185 offset:53248
	ds_read_b128 v[222:225], v185 offset:54272
	ds_read_b128 v[226:229], v185 offset:55296
	ds_read_b128 v[230:233], v185 offset:56320
	global_load_lds_dwordx4 v[194:195], off
	s_add_i32 m0, s44, 0x2000
	s_add_u32 s44, s84, 0x40080
	v_lshl_add_u64 v[194:195], v[234:235], 0, s[62:63]
	s_addc_u32 s45, s85, 0
	s_add_i32 s33, s33, s91
	global_load_lds_dwordx4 v[194:195], off
	s_nop 0
	s_mov_b32 m0, s33
	s_nop 0
	global_load_lds_dwordx4 v150, s[44:45]
	s_nop 0
	s_add_i32 m0, s33, 0x2000
	s_nop 0
	global_load_lds_dwordx4 v154, s[44:45]
	v_lshl_add_u64 v[194:195], v[236:237], 0, s[62:63]
	s_mov_b32 m0, s97
	s_nop 0
	global_load_lds_dwordx4 v[194:195], off
	v_lshl_add_u64 v[194:195], v[238:239], 0, s[62:63]
	s_mov_b32 m0, s98
	s_nop 0
	global_load_lds_dwordx4 v[194:195], off
	s_waitcnt vmcnt(8)
	s_waitcnt lgkmcnt(0)
	s_barrier
	s_setprio 1
	s_waitcnt lgkmcnt(0)
	v_mfma_f32_16x16x32_bf16 v[60:63], v[96:99], v[198:201], v[60:63]
	v_mfma_f32_16x16x32_bf16 v[56:59], v[112:115], v[198:201], v[56:59]
	v_mfma_f32_16x16x32_bf16 v[44:47], v[96:99], v[210:213], v[44:47]
	v_mfma_f32_16x16x32_bf16 v[40:43], v[112:115], v[210:213], v[40:43]
	v_mfma_f32_16x16x32_bf16 v[28:31], v[96:99], v[218:221], v[28:31]
	v_mfma_f32_16x16x32_bf16 v[24:27], v[112:115], v[218:221], v[24:27]
	v_mfma_f32_16x16x32_bf16 v[12:15], v[96:99], v[226:229], v[12:15]
	v_mfma_f32_16x16x32_bf16 v[8:11], v[112:115], v[226:229], v[8:11]
	v_mfma_f32_16x16x32_bf16 v[60:63], v[100:103], v[206:209], v[60:63]
	v_mfma_f32_16x16x32_bf16 v[56:59], v[120:123], v[206:209], v[56:59]
	v_mfma_f32_16x16x32_bf16 v[44:47], v[100:103], v[214:217], v[44:47]
	v_mfma_f32_16x16x32_bf16 v[40:43], v[120:123], v[214:217], v[40:43]
	v_mfma_f32_16x16x32_bf16 v[28:31], v[100:103], v[222:225], v[28:31]
	v_mfma_f32_16x16x32_bf16 v[24:27], v[120:123], v[222:225], v[24:27]
	v_mfma_f32_16x16x32_bf16 v[12:15], v[100:103], v[230:233], v[12:15]
	v_mfma_f32_16x16x32_bf16 v[8:11], v[120:123], v[230:233], v[8:11]
	s_setprio 0
	s_setprio 1
	v_mfma_f32_16x16x32_bf16 v[48:51], v[144:147], v[198:201], v[48:51]
	v_mfma_f32_16x16x32_bf16 v[52:55], v[186:189], v[198:201], v[52:55]
	v_mfma_f32_16x16x32_bf16 v[32:35], v[144:147], v[210:213], v[32:35]
	v_mfma_f32_16x16x32_bf16 v[36:39], v[186:189], v[210:213], v[36:39]
	v_mfma_f32_16x16x32_bf16 v[16:19], v[144:147], v[218:221], v[16:19]
	v_mfma_f32_16x16x32_bf16 v[20:23], v[186:189], v[218:221], v[20:23]
	v_mfma_f32_16x16x32_bf16 v[4:7], v[144:147], v[226:229], v[4:7]
	v_mfma_f32_16x16x32_bf16 v[0:3], v[186:189], v[226:229], v[0:3]
	v_mfma_f32_16x16x32_bf16 v[48:51], v[170:173], v[206:209], v[48:51]
	v_mfma_f32_16x16x32_bf16 v[52:55], v[190:193], v[206:209], v[52:55]
	v_mfma_f32_16x16x32_bf16 v[32:35], v[170:173], v[214:217], v[32:35]
	v_mfma_f32_16x16x32_bf16 v[36:39], v[190:193], v[214:217], v[36:39]
	v_mfma_f32_16x16x32_bf16 v[16:19], v[170:173], v[222:225], v[16:19]
	v_mfma_f32_16x16x32_bf16 v[20:23], v[190:193], v[222:225], v[20:23]
	v_mfma_f32_16x16x32_bf16 v[4:7], v[170:173], v[230:233], v[4:7]
	v_mfma_f32_16x16x32_bf16 v[0:3], v[190:193], v[230:233], v[0:3]
	s_setprio 0
	s_barrier
	s_add_i32 s89, s89, 2
	s_add_u32 s0, s0, 0x100
	s_addc_u32 s1, s1, 0
	s_add_u32 s14, s14, 0x100
	s_addc_u32 s15, s15, 0
	s_cmp_gt_u32 s89, 13
	s_cbranch_scc0 .LBB0_143
	s_and_b64 vcc, exec, s[64:65]
	s_cbranch_vccz .LBB0_146
	s_barrier

.LBB0_259:
	ds_read_b128 v[128:131], v171
	ds_read_b128 v[132:135], v171 offset:1024
	ds_read_b128 v[136:139], v171 offset:2048
	ds_read_b128 v[156:159], v171 offset:3072
	ds_read_b128 v[160:163], v172
	ds_read_b128 v[164:167], v172 offset:1024
	ds_read_b128 v[176:179], v172 offset:2048
	ds_read_b128 v[180:183], v172 offset:3072
	s_add_u32 s16, s12, 0xfffc0080
	s_addc_u32 s17, s13, -1
	s_cmp_eq_u32 s57, 12
	s_cselect_b32 s19, s1, s17
	s_cselect_b32 s18, s20, s16
	s_cselect_b32 s17, s21, s15
	s_cselect_b32 s16, s56, s14
	s_nop 0
	s_add_i32 m0, s83, 0xc000
	ds_read_b128 v[184:187], v173
	ds_read_b128 v[188:191], v173 offset:1024
	ds_read_b128 v[192:195], v173 offset:2048
	ds_read_b128 v[198:201], v173 offset:3072
	ds_read_b128 v[206:209], v173 offset:4096
	ds_read_b128 v[210:213], v173 offset:5120
	ds_read_b128 v[214:217], v173 offset:6144
	ds_read_b128 v[218:221], v173 offset:7168
	global_load_lds_dwordx4 v148, s[12:13]
	s_nop 0
	s_add_i32 m0, s83, 0xe000
	s_nop 0
	global_load_lds_dwordx4 v150, s[12:13]
	s_waitcnt vmcnt(8)
	s_waitcnt lgkmcnt(0)
	s_barrier
	s_setprio 1
	s_waitcnt lgkmcnt(0)
	v_mfma_f32_16x16x32_bf16 v[124:127], v[128:131], v[184:187], v[124:127]
	v_mfma_f32_16x16x32_bf16 v[120:123], v[136:139], v[184:187], v[120:123]
	v_mfma_f32_16x16x32_bf16 v[108:111], v[128:131], v[192:195], v[108:111]
	v_mfma_f32_16x16x32_bf16 v[104:107], v[136:139], v[192:195], v[104:107]
	v_mfma_f32_16x16x32_bf16 v[92:95], v[128:131], v[206:209], v[92:95]
	v_mfma_f32_16x16x32_bf16 v[88:91], v[136:139], v[206:209], v[88:91]
	v_mfma_f32_16x16x32_bf16 v[76:79], v[128:131], v[214:217], v[76:79]
	v_mfma_f32_16x16x32_bf16 v[72:75], v[136:139], v[214:217], v[72:75]
	v_mfma_f32_16x16x32_bf16 v[124:127], v[132:135], v[188:191], v[124:127]
	v_mfma_f32_16x16x32_bf16 v[120:123], v[156:159], v[188:191], v[120:123]
	v_mfma_f32_16x16x32_bf16 v[108:111], v[132:135], v[198:201], v[108:111]
	v_mfma_f32_16x16x32_bf16 v[104:107], v[156:159], v[198:201], v[104:107]
	v_mfma_f32_16x16x32_bf16 v[92:95], v[132:135], v[210:213], v[92:95]
	v_mfma_f32_16x16x32_bf16 v[88:91], v[156:159], v[210:213], v[88:91]
	v_mfma_f32_16x16x32_bf16 v[76:79], v[132:135], v[218:221], v[76:79]
	v_mfma_f32_16x16x32_bf16 v[72:75], v[156:159], v[218:221], v[72:75]
	s_setprio 0
	s_setprio 1
	v_mfma_f32_16x16x32_bf16 v[116:119], v[160:163], v[184:187], v[116:119]
	v_mfma_f32_16x16x32_bf16 v[112:115], v[176:179], v[184:187], v[112:115]
	v_mfma_f32_16x16x32_bf16 v[100:103], v[160:163], v[192:195], v[100:103]
	v_mfma_f32_16x16x32_bf16 v[96:99], v[176:179], v[192:195], v[96:99]
	v_mfma_f32_16x16x32_bf16 v[84:87], v[160:163], v[206:209], v[84:87]
	v_mfma_f32_16x16x32_bf16 v[80:83], v[176:179], v[206:209], v[80:83]
	v_mfma_f32_16x16x32_bf16 v[68:71], v[160:163], v[214:217], v[68:71]
	v_mfma_f32_16x16x32_bf16 v[64:67], v[176:179], v[214:217], v[64:67]
	v_mfma_f32_16x16x32_bf16 v[116:119], v[164:167], v[188:191], v[116:119]
	v_mfma_f32_16x16x32_bf16 v[112:115], v[180:183], v[188:191], v[112:115]
	v_mfma_f32_16x16x32_bf16 v[100:103], v[164:167], v[198:201], v[100:103]
	v_mfma_f32_16x16x32_bf16 v[96:99], v[180:183], v[198:201], v[96:99]
	v_mfma_f32_16x16x32_bf16 v[84:87], v[164:167], v[210:213], v[84:87]
	v_mfma_f32_16x16x32_bf16 v[80:83], v[180:183], v[210:213], v[80:83]
	v_mfma_f32_16x16x32_bf16 v[68:71], v[164:167], v[218:221], v[68:71]
	v_mfma_f32_16x16x32_bf16 v[64:67], v[180:183], v[218:221], v[64:67]
	s_setprio 0
	s_barrier
	s_add_i32 s33, s93, s82
	v_lshl_add_u64 v[222:223], s[16:17], 0, v[142:143]
	s_mov_b32 m0, s33
	ds_read_b128 v[184:187], v173 offset:16384
	ds_read_b128 v[188:191], v173 offset:17408
	ds_read_b128 v[192:195], v173 offset:18432
	ds_read_b128 v[198:201], v173 offset:19456
	ds_read_b128 v[206:209], v173 offset:20480
	ds_read_b128 v[210:213], v173 offset:21504
	ds_read_b128 v[214:217], v173 offset:22528
	ds_read_b128 v[218:221], v173 offset:23552
	global_load_lds_dwordx4 v[222:223], off
	s_add_i32 m0, s33, 0x2000
	s_add_u32 s44, s16, 0x40000
	v_lshl_add_u64 v[224:225], s[16:17], 0, v[146:147]
	s_addc_u32 s45, s17, 0
	s_add_i32 s33, s94, s82
	global_load_lds_dwordx4 v[224:225], off
	s_nop 0
	s_mov_b32 m0, s33
	v_lshl_add_u64 v[228:229], s[18:19], 0, v[144:145]
	global_load_lds_dwordx4 v142, s[44:45]
	s_nop 0
	s_add_i32 m0, s33, 0x2000
	s_nop 0
	global_load_lds_dwordx4 v146, s[44:45]
	v_lshl_add_u64 v[226:227], s[18:19], 0, v[140:141]
	s_mov_b32 m0, s83
	s_nop 0
	global_load_lds_dwordx4 v[226:227], off
	s_mov_b32 m0, s84
	s_nop 0
	global_load_lds_dwordx4 v[228:229], off
	s_waitcnt vmcnt(8)
	s_waitcnt lgkmcnt(0)
	s_barrier
	s_setprio 1
	s_waitcnt lgkmcnt(0)
	v_mfma_f32_16x16x32_bf16 v[60:63], v[128:131], v[184:187], v[60:63]
	v_mfma_f32_16x16x32_bf16 v[56:59], v[136:139], v[184:187], v[56:59]
	v_mfma_f32_16x16x32_bf16 v[44:47], v[128:131], v[192:195], v[44:47]
	v_mfma_f32_16x16x32_bf16 v[40:43], v[136:139], v[192:195], v[40:43]
	v_mfma_f32_16x16x32_bf16 v[28:31], v[128:131], v[206:209], v[28:31]
	v_mfma_f32_16x16x32_bf16 v[24:27], v[136:139], v[206:209], v[24:27]
	v_mfma_f32_16x16x32_bf16 v[12:15], v[128:131], v[214:217], v[12:15]
	v_mfma_f32_16x16x32_bf16 v[8:11], v[136:139], v[214:217], v[8:11]
	v_mfma_f32_16x16x32_bf16 v[60:63], v[132:135], v[188:191], v[60:63]
	v_mfma_f32_16x16x32_bf16 v[56:59], v[156:159], v[188:191], v[56:59]
	v_mfma_f32_16x16x32_bf16 v[44:47], v[132:135], v[198:201], v[44:47]
	v_mfma_f32_16x16x32_bf16 v[40:43], v[156:159], v[198:201], v[40:43]
	v_mfma_f32_16x16x32_bf16 v[28:31], v[132:135], v[210:213], v[28:31]
	v_mfma_f32_16x16x32_bf16 v[24:27], v[156:159], v[210:213], v[24:27]
	v_mfma_f32_16x16x32_bf16 v[12:15], v[132:135], v[218:221], v[12:15]
	v_mfma_f32_16x16x32_bf16 v[8:11], v[156:159], v[218:221], v[8:11]
	s_setprio 0
	s_setprio 1
	v_mfma_f32_16x16x32_bf16 v[52:55], v[160:163], v[184:187], v[52:55]
	v_mfma_f32_16x16x32_bf16 v[48:51], v[176:179], v[184:187], v[48:51]
	v_mfma_f32_16x16x32_bf16 v[36:39], v[160:163], v[192:195], v[36:39]
	v_mfma_f32_16x16x32_bf16 v[32:35], v[176:179], v[192:195], v[32:35]
	v_mfma_f32_16x16x32_bf16 v[20:23], v[160:163], v[206:209], v[20:23]
	v_mfma_f32_16x16x32_bf16 v[16:19], v[176:179], v[206:209], v[16:19]
	v_mfma_f32_16x16x32_bf16 v[4:7], v[160:163], v[214:217], v[4:7]
	v_mfma_f32_16x16x32_bf16 v[0:3], v[176:179], v[214:217], v[0:3]
	v_mfma_f32_16x16x32_bf16 v[52:55], v[164:167], v[188:191], v[52:55]
	v_mfma_f32_16x16x32_bf16 v[48:51], v[180:183], v[188:191], v[48:51]
	v_mfma_f32_16x16x32_bf16 v[36:39], v[164:167], v[198:201], v[36:39]
	v_mfma_f32_16x16x32_bf16 v[32:35], v[180:183], v[198:201], v[32:35]
	v_mfma_f32_16x16x32_bf16 v[20:23], v[164:167], v[210:213], v[20:23]
	v_mfma_f32_16x16x32_bf16 v[16:19], v[180:183], v[210:213], v[16:19]
	v_mfma_f32_16x16x32_bf16 v[4:7], v[164:167], v[218:221], v[4:7]
	v_mfma_f32_16x16x32_bf16 v[0:3], v[180:183], v[218:221], v[0:3]
	s_setprio 0
	s_barrier
	s_add_i32 s33, 0, 0x18000
	s_add_i32 s44, 0, 0x1c000
	v_add_u32_e32 v156, s33, v169
	v_add_u32_e32 v175, s44, v169
	ds_read_b128 v[128:131], v156
	ds_read_b128 v[132:135], v156 offset:1024
	ds_read_b128 v[136:139], v156 offset:2048
	ds_read_b128 v[156:159], v156 offset:3072
	ds_read_b128 v[160:163], v175
	ds_read_b128 v[164:167], v175 offset:1024
	ds_read_b128 v[176:179], v175 offset:2048
	ds_read_b128 v[180:183], v175 offset:3072
	s_add_u32 s18, s18, 0x40000
	s_addc_u32 s19, s19, 0
	s_mov_b32 m0, s85
	s_nop 0
	ds_read_b128 v[184:187], v173 offset:32768
	ds_read_b128 v[188:191], v173 offset:33792
	ds_read_b128 v[192:195], v173 offset:34816
	ds_read_b128 v[198:201], v173 offset:35840
	ds_read_b128 v[206:209], v173 offset:36864
	ds_read_b128 v[210:213], v173 offset:37888
	ds_read_b128 v[214:217], v173 offset:38912
	ds_read_b128 v[218:221], v173 offset:39936
	global_load_lds_dwordx4 v140, s[18:19]
	s_nop 0
	s_mov_b32 m0, s86
	s_nop 0
	global_load_lds_dwordx4 v144, s[18:19]
	s_waitcnt vmcnt(8)
	s_waitcnt lgkmcnt(0)
	s_barrier
	s_setprio 1
	s_waitcnt lgkmcnt(0)
	v_mfma_f32_16x16x32_bf16 v[124:127], v[128:131], v[184:187], v[124:127]
	v_mfma_f32_16x16x32_bf16 v[120:123], v[136:139], v[184:187], v[120:123]
	v_mfma_f32_16x16x32_bf16 v[108:111], v[128:131], v[192:195], v[108:111]
	v_mfma_f32_16x16x32_bf16 v[104:107], v[136:139], v[192:195], v[104:107]
	v_mfma_f32_16x16x32_bf16 v[92:95], v[128:131], v[206:209], v[92:95]
	v_mfma_f32_16x16x32_bf16 v[88:91], v[136:139], v[206:209], v[88:91]
	v_mfma_f32_16x16x32_bf16 v[76:79], v[128:131], v[214:217], v[76:79]
	v_mfma_f32_16x16x32_bf16 v[72:75], v[136:139], v[214:217], v[72:75]
	v_mfma_f32_16x16x32_bf16 v[124:127], v[132:135], v[188:191], v[124:127]
	v_mfma_f32_16x16x32_bf16 v[120:123], v[156:159], v[188:191], v[120:123]
	v_mfma_f32_16x16x32_bf16 v[108:111], v[132:135], v[198:201], v[108:111]
	v_mfma_f32_16x16x32_bf16 v[104:107], v[156:159], v[198:201], v[104:107]
	v_mfma_f32_16x16x32_bf16 v[92:95], v[132:135], v[210:213], v[92:95]
	v_mfma_f32_16x16x32_bf16 v[88:91], v[156:159], v[210:213], v[88:91]
	v_mfma_f32_16x16x32_bf16 v[76:79], v[132:135], v[218:221], v[76:79]
	v_mfma_f32_16x16x32_bf16 v[72:75], v[156:159], v[218:221], v[72:75]
	s_setprio 0
	s_setprio 1
	v_mfma_f32_16x16x32_bf16 v[116:119], v[160:163], v[184:187], v[116:119]
	v_mfma_f32_16x16x32_bf16 v[112:115], v[176:179], v[184:187], v[112:115]
	v_mfma_f32_16x16x32_bf16 v[100:103], v[160:163], v[192:195], v[100:103]
	v_mfma_f32_16x16x32_bf16 v[96:99], v[176:179], v[192:195], v[96:99]
	v_mfma_f32_16x16x32_bf16 v[84:87], v[160:163], v[206:209], v[84:87]
	v_mfma_f32_16x16x32_bf16 v[80:83], v[176:179], v[206:209], v[80:83]
	v_mfma_f32_16x16x32_bf16 v[68:71], v[160:163], v[214:217], v[68:71]
	v_mfma_f32_16x16x32_bf16 v[64:67], v[176:179], v[214:217], v[64:67]
	v_mfma_f32_16x16x32_bf16 v[116:119], v[164:167], v[188:191], v[116:119]
	v_mfma_f32_16x16x32_bf16 v[112:115], v[180:183], v[188:191], v[112:115]
	v_mfma_f32_16x16x32_bf16 v[100:103], v[164:167], v[198:201], v[100:103]
	v_mfma_f32_16x16x32_bf16 v[96:99], v[180:183], v[198:201], v[96:99]
	v_mfma_f32_16x16x32_bf16 v[84:87], v[164:167], v[210:213], v[84:87]
	v_mfma_f32_16x16x32_bf16 v[80:83], v[180:183], v[210:213], v[80:83]
	v_mfma_f32_16x16x32_bf16 v[68:71], v[164:167], v[218:221], v[68:71]
	v_mfma_f32_16x16x32_bf16 v[64:67], v[180:183], v[218:221], v[64:67]
	s_setprio 0
	s_barrier
	s_add_i32 s18, s33, s82
	v_lshl_add_u64 v[222:223], v[222:223], 0, s[68:69]
	s_mov_b32 m0, s18
	ds_read_b128 v[184:187], v173 offset:49152
	ds_read_b128 v[188:191], v173 offset:50176
	ds_read_b128 v[192:195], v173 offset:51200
	ds_read_b128 v[198:201], v173 offset:52224
	ds_read_b128 v[206:209], v173 offset:53248
	ds_read_b128 v[210:213], v173 offset:54272
	ds_read_b128 v[214:217], v173 offset:55296
	ds_read_b128 v[218:221], v173 offset:56320
	global_load_lds_dwordx4 v[222:223], off
	s_add_i32 m0, s18, 0x2000
	s_add_u32 s16, s16, 0x40080
	v_lshl_add_u64 v[222:223], v[224:225], 0, s[68:69]
	s_addc_u32 s17, s17, 0
	s_add_i32 s18, s44, s82
	global_load_lds_dwordx4 v[222:223], off
	s_nop 0
	s_mov_b32 m0, s18
	s_nop 0
	global_load_lds_dwordx4 v142, s[16:17]
	s_nop 0
	s_add_i32 m0, s18, 0x2000
	s_nop 0
	global_load_lds_dwordx4 v146, s[16:17]
	v_lshl_add_u64 v[222:223], v[226:227], 0, s[68:69]
	s_mov_b32 m0, s91
	s_nop 0
	global_load_lds_dwordx4 v[222:223], off
	v_lshl_add_u64 v[222:223], v[228:229], 0, s[68:69]
	s_mov_b32 m0, s92
	s_nop 0
	global_load_lds_dwordx4 v[222:223], off
	s_waitcnt vmcnt(8)
	s_waitcnt lgkmcnt(0)
	s_barrier
	s_setprio 1
	s_waitcnt lgkmcnt(0)
	v_mfma_f32_16x16x32_bf16 v[60:63], v[128:131], v[184:187], v[60:63]
	v_mfma_f32_16x16x32_bf16 v[56:59], v[136:139], v[184:187], v[56:59]
	v_mfma_f32_16x16x32_bf16 v[44:47], v[128:131], v[192:195], v[44:47]
	v_mfma_f32_16x16x32_bf16 v[40:43], v[136:139], v[192:195], v[40:43]
	v_mfma_f32_16x16x32_bf16 v[28:31], v[128:131], v[206:209], v[28:31]
	v_mfma_f32_16x16x32_bf16 v[24:27], v[136:139], v[206:209], v[24:27]
	v_mfma_f32_16x16x32_bf16 v[12:15], v[128:131], v[214:217], v[12:15]
	v_mfma_f32_16x16x32_bf16 v[8:11], v[136:139], v[214:217], v[8:11]
	v_mfma_f32_16x16x32_bf16 v[60:63], v[132:135], v[188:191], v[60:63]
	v_mfma_f32_16x16x32_bf16 v[56:59], v[156:159], v[188:191], v[56:59]
	v_mfma_f32_16x16x32_bf16 v[44:47], v[132:135], v[198:201], v[44:47]
	v_mfma_f32_16x16x32_bf16 v[40:43], v[156:159], v[198:201], v[40:43]
	v_mfma_f32_16x16x32_bf16 v[28:31], v[132:135], v[210:213], v[28:31]
	v_mfma_f32_16x16x32_bf16 v[24:27], v[156:159], v[210:213], v[24:27]
	v_mfma_f32_16x16x32_bf16 v[12:15], v[132:135], v[218:221], v[12:15]
	v_mfma_f32_16x16x32_bf16 v[8:11], v[156:159], v[218:221], v[8:11]
	s_setprio 0
	s_setprio 1
	v_mfma_f32_16x16x32_bf16 v[52:55], v[160:163], v[184:187], v[52:55]
	v_mfma_f32_16x16x32_bf16 v[48:51], v[176:179], v[184:187], v[48:51]
	v_mfma_f32_16x16x32_bf16 v[36:39], v[160:163], v[192:195], v[36:39]
	v_mfma_f32_16x16x32_bf16 v[32:35], v[176:179], v[192:195], v[32:35]
	v_mfma_f32_16x16x32_bf16 v[20:23], v[160:163], v[206:209], v[20:23]
	v_mfma_f32_16x16x32_bf16 v[16:19], v[176:179], v[206:209], v[16:19]
	v_mfma_f32_16x16x32_bf16 v[4:7], v[160:163], v[214:217], v[4:7]
	v_mfma_f32_16x16x32_bf16 v[0:3], v[176:179], v[214:217], v[0:3]
	v_mfma_f32_16x16x32_bf16 v[52:55], v[164:167], v[188:191], v[52:55]
	v_mfma_f32_16x16x32_bf16 v[48:51], v[180:183], v[188:191], v[48:51]
	v_mfma_f32_16x16x32_bf16 v[36:39], v[164:167], v[198:201], v[36:39]
	v_mfma_f32_16x16x32_bf16 v[32:35], v[180:183], v[198:201], v[32:35]
	v_mfma_f32_16x16x32_bf16 v[20:23], v[164:167], v[210:213], v[20:23]
	v_mfma_f32_16x16x32_bf16 v[16:19], v[180:183], v[210:213], v[16:19]
	v_mfma_f32_16x16x32_bf16 v[4:7], v[164:167], v[218:221], v[4:7]
	v_mfma_f32_16x16x32_bf16 v[0:3], v[180:183], v[218:221], v[0:3]
	s_setprio 0
	s_barrier
	s_add_i32 s57, s57, 2
	s_add_u32 s12, s12, 0x100
	s_addc_u32 s13, s13, 0
	s_add_u32 s14, s14, 0x100
	s_addc_u32 s15, s15, 0
	s_cmp_gt_u32 s57, 13
	s_cbranch_scc0 .LBB0_259
	s_and_b64 vcc, exec, s[70:71]
	s_cbranch_vccz .LBB0_262
	s_barrier

.LBB0_374:
	ds_read_b128 v[32:35], v208
	ds_read_b128 v[36:39], v208 offset:1024
	ds_read_b128 v[40:43], v208 offset:2048
	ds_read_b128 v[44:47], v208 offset:3072
	ds_read_b128 v[144:147], v209
	ds_read_b128 v[148:151], v209 offset:1024
	ds_read_b128 v[152:155], v209 offset:2048
	ds_read_b128 v[156:159], v209 offset:3072
	s_add_u32 s33, s68, 0xfffc0080
	s_addc_u32 s57, s69, -1
	s_cmp_eq_u32 s56, 12
	s_cselect_b32 s73, s11, s57
	s_cselect_b32 s72, s13, s33
	s_cselect_b32 s71, s21, s15
	s_cselect_b32 s70, s23, s14
	s_nop 0
	s_add_i32 m0, s77, 0xc000
	ds_read_b128 v[182:185], v210
	ds_read_b128 v[186:189], v210 offset:1024
	ds_read_b128 v[190:193], v210 offset:2048
	ds_read_b128 v[198:201], v210 offset:3072
	ds_read_b128 v[214:217], v210 offset:4096
	ds_read_b128 v[218:221], v210 offset:5120
	ds_read_b128 v[222:225], v210 offset:6144
	ds_read_b128 v[226:229], v210 offset:7168
	global_load_lds_dwordx4 v174, s[68:69]
	s_nop 0
	s_add_i32 m0, s77, 0xe000
	s_nop 0
	global_load_lds_dwordx4 v176, s[68:69]
	s_waitcnt vmcnt(8)
	s_waitcnt lgkmcnt(0)
	s_barrier
	s_setprio 1
	s_waitcnt lgkmcnt(0)
	v_mfma_f32_16x16x32_bf16 v[140:143], v[32:35], v[182:185], v[140:143]
	v_mfma_f32_16x16x32_bf16 v[136:139], v[40:43], v[182:185], v[136:139]
	v_mfma_f32_16x16x32_bf16 v[124:127], v[32:35], v[190:193], v[124:127]
	v_mfma_f32_16x16x32_bf16 v[120:123], v[40:43], v[190:193], v[120:123]
	v_mfma_f32_16x16x32_bf16 v[108:111], v[32:35], v[214:217], v[108:111]
	v_mfma_f32_16x16x32_bf16 v[104:107], v[40:43], v[214:217], v[104:107]
	v_mfma_f32_16x16x32_bf16 v[92:95], v[32:35], v[222:225], v[92:95]
	v_mfma_f32_16x16x32_bf16 v[88:91], v[40:43], v[222:225], v[88:91]
	v_mfma_f32_16x16x32_bf16 v[140:143], v[36:39], v[186:189], v[140:143]
	v_mfma_f32_16x16x32_bf16 v[136:139], v[44:47], v[186:189], v[136:139]
	v_mfma_f32_16x16x32_bf16 v[124:127], v[36:39], v[198:201], v[124:127]
	v_mfma_f32_16x16x32_bf16 v[120:123], v[44:47], v[198:201], v[120:123]
	v_mfma_f32_16x16x32_bf16 v[108:111], v[36:39], v[218:221], v[108:111]
	v_mfma_f32_16x16x32_bf16 v[104:107], v[44:47], v[218:221], v[104:107]
	v_mfma_f32_16x16x32_bf16 v[92:95], v[36:39], v[226:229], v[92:95]
	v_mfma_f32_16x16x32_bf16 v[88:91], v[44:47], v[226:229], v[88:91]
	s_setprio 0
	s_setprio 1
	v_mfma_f32_16x16x32_bf16 v[132:135], v[144:147], v[182:185], v[132:135]
	v_mfma_f32_16x16x32_bf16 v[128:131], v[152:155], v[182:185], v[128:131]
	v_mfma_f32_16x16x32_bf16 v[116:119], v[144:147], v[190:193], v[116:119]
	v_mfma_f32_16x16x32_bf16 v[112:115], v[152:155], v[190:193], v[112:115]
	v_mfma_f32_16x16x32_bf16 v[100:103], v[144:147], v[214:217], v[100:103]
	v_mfma_f32_16x16x32_bf16 v[96:99], v[152:155], v[214:217], v[96:99]
	v_mfma_f32_16x16x32_bf16 v[84:87], v[144:147], v[222:225], v[84:87]
	v_mfma_f32_16x16x32_bf16 v[80:83], v[152:155], v[222:225], v[80:83]
	v_mfma_f32_16x16x32_bf16 v[132:135], v[148:151], v[186:189], v[132:135]
	v_mfma_f32_16x16x32_bf16 v[128:131], v[156:159], v[186:189], v[128:131]
	v_mfma_f32_16x16x32_bf16 v[116:119], v[148:151], v[198:201], v[116:119]
	v_mfma_f32_16x16x32_bf16 v[112:115], v[156:159], v[198:201], v[112:115]
	v_mfma_f32_16x16x32_bf16 v[100:103], v[148:151], v[218:221], v[100:103]
	v_mfma_f32_16x16x32_bf16 v[96:99], v[156:159], v[218:221], v[96:99]
	v_mfma_f32_16x16x32_bf16 v[84:87], v[148:151], v[226:229], v[84:87]
	v_mfma_f32_16x16x32_bf16 v[80:83], v[156:159], v[226:229], v[80:83]
	s_setprio 0
	s_barrier
	s_add_i32 s33, s87, s76
	v_lshl_add_u64 v[194:195], s[70:71], 0, v[162:163]
	s_mov_b32 m0, s33
	ds_read_b128 v[182:185], v210 offset:16384
	ds_read_b128 v[186:189], v210 offset:17408
	ds_read_b128 v[190:193], v210 offset:18432
	ds_read_b128 v[198:201], v210 offset:19456
	ds_read_b128 v[214:217], v210 offset:20480
	ds_read_b128 v[218:221], v210 offset:21504
	ds_read_b128 v[222:225], v210 offset:22528
	ds_read_b128 v[226:229], v210 offset:23552
	global_load_lds_dwordx4 v[194:195], off
	s_add_i32 m0, s33, 0x2000
	s_add_u32 s88, s70, 0x40000
	v_lshl_add_u64 v[230:231], s[70:71], 0, v[166:167]
	s_addc_u32 s89, s71, 0
	s_add_i32 s33, s91, s76
	global_load_lds_dwordx4 v[230:231], off
	s_nop 0
	s_mov_b32 m0, s33
	v_lshl_add_u64 v[234:235], s[72:73], 0, v[164:165]
	global_load_lds_dwordx4 v162, s[88:89]
	s_nop 0
	s_add_i32 m0, s33, 0x2000
	s_nop 0
	global_load_lds_dwordx4 v166, s[88:89]
	v_lshl_add_u64 v[232:233], s[72:73], 0, v[160:161]
	s_mov_b32 m0, s77
	s_nop 0
	global_load_lds_dwordx4 v[232:233], off
	s_mov_b32 m0, s78
	s_nop 0
	global_load_lds_dwordx4 v[234:235], off
	s_waitcnt vmcnt(8)
	s_waitcnt lgkmcnt(0)
	s_barrier
	s_setprio 1
	s_waitcnt lgkmcnt(0)
	v_mfma_f32_16x16x32_bf16 v[76:79], v[32:35], v[182:185], v[76:79]
	v_mfma_f32_16x16x32_bf16 v[72:75], v[40:43], v[182:185], v[72:75]
	v_mfma_f32_16x16x32_bf16 v[60:63], v[32:35], v[190:193], v[60:63]
	v_mfma_f32_16x16x32_bf16 v[56:59], v[40:43], v[190:193], v[56:59]
	v_mfma_f32_16x16x32_bf16 v[28:31], v[32:35], v[214:217], v[28:31]
	v_mfma_f32_16x16x32_bf16 v[24:27], v[40:43], v[214:217], v[24:27]
	v_mfma_f32_16x16x32_bf16 v[12:15], v[32:35], v[222:225], v[12:15]
	v_mfma_f32_16x16x32_bf16 v[8:11], v[40:43], v[222:225], v[8:11]
	v_mfma_f32_16x16x32_bf16 v[76:79], v[36:39], v[186:189], v[76:79]
	v_mfma_f32_16x16x32_bf16 v[72:75], v[44:47], v[186:189], v[72:75]
	v_mfma_f32_16x16x32_bf16 v[60:63], v[36:39], v[198:201], v[60:63]
	v_mfma_f32_16x16x32_bf16 v[56:59], v[44:47], v[198:201], v[56:59]
	v_mfma_f32_16x16x32_bf16 v[28:31], v[36:39], v[218:221], v[28:31]
	v_mfma_f32_16x16x32_bf16 v[24:27], v[44:47], v[218:221], v[24:27]
	v_mfma_f32_16x16x32_bf16 v[12:15], v[36:39], v[226:229], v[12:15]
	v_mfma_f32_16x16x32_bf16 v[8:11], v[44:47], v[226:229], v[8:11]
	s_setprio 0
	s_setprio 1
	v_mfma_f32_16x16x32_bf16 v[20:23], v[144:147], v[214:217], v[20:23]
	v_mfma_f32_16x16x32_bf16 v[16:19], v[152:155], v[214:217], v[16:19]
	v_mfma_f32_16x16x32_bf16 v[4:7], v[144:147], v[222:225], v[4:7]
	v_mfma_f32_16x16x32_bf16 v[0:3], v[152:155], v[222:225], v[0:3]
	v_mfma_f32_16x16x32_bf16 v[32:35], v[144:147], v[182:185], v[68:71]
	v_mfma_f32_16x16x32_bf16 v[36:39], v[152:155], v[182:185], v[64:67]
	v_mfma_f32_16x16x32_bf16 v[40:43], v[144:147], v[190:193], v[52:55]
	v_mfma_f32_16x16x32_bf16 v[44:47], v[152:155], v[190:193], v[48:51]
	v_mfma_f32_16x16x32_bf16 v[20:23], v[148:151], v[218:221], v[20:23]
	v_mfma_f32_16x16x32_bf16 v[16:19], v[156:159], v[218:221], v[16:19]
	v_mfma_f32_16x16x32_bf16 v[4:7], v[148:151], v[226:229], v[4:7]
	v_mfma_f32_16x16x32_bf16 v[0:3], v[156:159], v[226:229], v[0:3]
	v_mfma_f32_16x16x32_bf16 v[32:35], v[148:151], v[186:189], v[32:35]
	v_mfma_f32_16x16x32_bf16 v[36:39], v[156:159], v[186:189], v[36:39]
	v_mfma_f32_16x16x32_bf16 v[40:43], v[148:151], v[198:201], v[40:43]
	v_mfma_f32_16x16x32_bf16 v[44:47], v[156:159], v[198:201], v[44:47]
	s_setprio 0
	s_barrier
	s_add_i32 s33, 0, 0x18000
	s_add_i32 s57, 0, 0x1c000
	v_add_u32_e32 v68, s33, v207
	v_add_u32_e32 v156, s57, v207
	ds_read_b128 v[48:51], v68
	ds_read_b128 v[52:55], v68 offset:1024
	ds_read_b128 v[64:67], v68 offset:2048
	ds_read_b128 v[68:71], v68 offset:3072
	ds_read_b128 v[144:147], v156
	ds_read_b128 v[148:151], v156 offset:1024
	ds_read_b128 v[152:155], v156 offset:2048
	ds_read_b128 v[156:159], v156 offset:3072
	s_add_u32 s72, s72, 0x40000
	s_addc_u32 s73, s73, 0
	s_mov_b32 m0, s79
	s_nop 0
	ds_read_b128 v[182:185], v210 offset:32768
	ds_read_b128 v[186:189], v210 offset:33792
	ds_read_b128 v[190:193], v210 offset:34816
	ds_read_b128 v[198:201], v210 offset:35840
	ds_read_b128 v[214:217], v210 offset:36864
	ds_read_b128 v[218:221], v210 offset:37888
	ds_read_b128 v[222:225], v210 offset:38912
	ds_read_b128 v[226:229], v210 offset:39936
	global_load_lds_dwordx4 v160, s[72:73]
	s_nop 0
	s_mov_b32 m0, s82
	s_nop 0
	global_load_lds_dwordx4 v164, s[72:73]
	s_waitcnt vmcnt(8)
	s_waitcnt lgkmcnt(0)
	s_barrier
	s_setprio 1
	s_waitcnt lgkmcnt(0)
	v_mfma_f32_16x16x32_bf16 v[140:143], v[48:51], v[182:185], v[140:143]
	v_mfma_f32_16x16x32_bf16 v[136:139], v[64:67], v[182:185], v[136:139]
	v_mfma_f32_16x16x32_bf16 v[124:127], v[48:51], v[190:193], v[124:127]
	v_mfma_f32_16x16x32_bf16 v[120:123], v[64:67], v[190:193], v[120:123]
	v_mfma_f32_16x16x32_bf16 v[108:111], v[48:51], v[214:217], v[108:111]
	v_mfma_f32_16x16x32_bf16 v[104:107], v[64:67], v[214:217], v[104:107]
	v_mfma_f32_16x16x32_bf16 v[92:95], v[48:51], v[222:225], v[92:95]
	v_mfma_f32_16x16x32_bf16 v[88:91], v[64:67], v[222:225], v[88:91]
	v_mfma_f32_16x16x32_bf16 v[140:143], v[52:55], v[186:189], v[140:143]
	v_mfma_f32_16x16x32_bf16 v[136:139], v[68:71], v[186:189], v[136:139]
	v_mfma_f32_16x16x32_bf16 v[124:127], v[52:55], v[198:201], v[124:127]
	v_mfma_f32_16x16x32_bf16 v[120:123], v[68:71], v[198:201], v[120:123]
	v_mfma_f32_16x16x32_bf16 v[108:111], v[52:55], v[218:221], v[108:111]
	v_mfma_f32_16x16x32_bf16 v[104:107], v[68:71], v[218:221], v[104:107]
	v_mfma_f32_16x16x32_bf16 v[92:95], v[52:55], v[226:229], v[92:95]
	v_mfma_f32_16x16x32_bf16 v[88:91], v[68:71], v[226:229], v[88:91]
	s_setprio 0
	s_setprio 1
	v_mfma_f32_16x16x32_bf16 v[132:135], v[144:147], v[182:185], v[132:135]
	v_mfma_f32_16x16x32_bf16 v[128:131], v[152:155], v[182:185], v[128:131]
	v_mfma_f32_16x16x32_bf16 v[116:119], v[144:147], v[190:193], v[116:119]
	v_mfma_f32_16x16x32_bf16 v[112:115], v[152:155], v[190:193], v[112:115]
	v_mfma_f32_16x16x32_bf16 v[100:103], v[144:147], v[214:217], v[100:103]
	v_mfma_f32_16x16x32_bf16 v[96:99], v[152:155], v[214:217], v[96:99]
	v_mfma_f32_16x16x32_bf16 v[84:87], v[144:147], v[222:225], v[84:87]
	v_mfma_f32_16x16x32_bf16 v[80:83], v[152:155], v[222:225], v[80:83]
	v_mfma_f32_16x16x32_bf16 v[132:135], v[148:151], v[186:189], v[132:135]
	v_mfma_f32_16x16x32_bf16 v[128:131], v[156:159], v[186:189], v[128:131]
	v_mfma_f32_16x16x32_bf16 v[116:119], v[148:151], v[198:201], v[116:119]
	v_mfma_f32_16x16x32_bf16 v[112:115], v[156:159], v[198:201], v[112:115]
	v_mfma_f32_16x16x32_bf16 v[100:103], v[148:151], v[218:221], v[100:103]
	v_mfma_f32_16x16x32_bf16 v[96:99], v[156:159], v[218:221], v[96:99]
	v_mfma_f32_16x16x32_bf16 v[84:87], v[148:151], v[226:229], v[84:87]
	v_mfma_f32_16x16x32_bf16 v[80:83], v[156:159], v[226:229], v[80:83]
	s_setprio 0
	s_barrier
	s_add_i32 s33, s33, s76
	v_lshl_add_u64 v[194:195], v[194:195], 0, s[16:17]
	s_mov_b32 m0, s33
	ds_read_b128 v[182:185], v210 offset:49152
	ds_read_b128 v[186:189], v210 offset:50176
	ds_read_b128 v[190:193], v210 offset:51200
	ds_read_b128 v[198:201], v210 offset:52224
	ds_read_b128 v[214:217], v210 offset:53248
	ds_read_b128 v[218:221], v210 offset:54272
	ds_read_b128 v[222:225], v210 offset:55296
	ds_read_b128 v[226:229], v210 offset:56320
	global_load_lds_dwordx4 v[194:195], off
	s_add_i32 m0, s33, 0x2000
	s_add_u32 s70, s70, 0x40080
	v_lshl_add_u64 v[194:195], v[230:231], 0, s[16:17]
	s_addc_u32 s71, s71, 0
	s_add_i32 s33, s57, s76
	global_load_lds_dwordx4 v[194:195], off
	s_nop 0
	s_mov_b32 m0, s33
	s_nop 0
	global_load_lds_dwordx4 v162, s[70:71]
	s_nop 0
	s_add_i32 m0, s33, 0x2000
	s_nop 0
	global_load_lds_dwordx4 v166, s[70:71]
	v_lshl_add_u64 v[194:195], v[232:233], 0, s[16:17]
	s_mov_b32 m0, s85
	s_nop 0
	global_load_lds_dwordx4 v[194:195], off
	v_lshl_add_u64 v[194:195], v[234:235], 0, s[16:17]
	s_mov_b32 m0, s86
	s_nop 0
	global_load_lds_dwordx4 v[194:195], off
	s_waitcnt vmcnt(8)
	s_waitcnt lgkmcnt(0)
	s_barrier
	s_setprio 1
	s_waitcnt lgkmcnt(0)
	v_mfma_f32_16x16x32_bf16 v[76:79], v[48:51], v[182:185], v[76:79]
	v_mfma_f32_16x16x32_bf16 v[72:75], v[64:67], v[182:185], v[72:75]
	v_mfma_f32_16x16x32_bf16 v[60:63], v[48:51], v[190:193], v[60:63]
	v_mfma_f32_16x16x32_bf16 v[56:59], v[64:67], v[190:193], v[56:59]
	v_mfma_f32_16x16x32_bf16 v[28:31], v[48:51], v[214:217], v[28:31]
	v_mfma_f32_16x16x32_bf16 v[24:27], v[64:67], v[214:217], v[24:27]
	v_mfma_f32_16x16x32_bf16 v[12:15], v[48:51], v[222:225], v[12:15]
	v_mfma_f32_16x16x32_bf16 v[8:11], v[64:67], v[222:225], v[8:11]
	v_mfma_f32_16x16x32_bf16 v[76:79], v[52:55], v[186:189], v[76:79]
	v_mfma_f32_16x16x32_bf16 v[72:75], v[68:71], v[186:189], v[72:75]
	v_mfma_f32_16x16x32_bf16 v[60:63], v[52:55], v[198:201], v[60:63]
	v_mfma_f32_16x16x32_bf16 v[56:59], v[68:71], v[198:201], v[56:59]
	v_mfma_f32_16x16x32_bf16 v[28:31], v[52:55], v[218:221], v[28:31]
	v_mfma_f32_16x16x32_bf16 v[24:27], v[68:71], v[218:221], v[24:27]
	v_mfma_f32_16x16x32_bf16 v[12:15], v[52:55], v[226:229], v[12:15]
	v_mfma_f32_16x16x32_bf16 v[8:11], v[68:71], v[226:229], v[8:11]
	s_setprio 0
	s_setprio 1
	v_mfma_f32_16x16x32_bf16 v[32:35], v[144:147], v[182:185], v[32:35]
	v_mfma_f32_16x16x32_bf16 v[68:71], v[148:151], v[186:189], v[32:35]
	v_mfma_f32_16x16x32_bf16 v[32:35], v[152:155], v[182:185], v[36:39]
	v_mfma_f32_16x16x32_bf16 v[64:67], v[156:159], v[186:189], v[32:35]
	v_mfma_f32_16x16x32_bf16 v[32:35], v[144:147], v[190:193], v[40:43]
	v_mfma_f32_16x16x32_bf16 v[52:55], v[148:151], v[198:201], v[32:35]
	v_mfma_f32_16x16x32_bf16 v[32:35], v[152:155], v[190:193], v[44:47]
	v_mfma_f32_16x16x32_bf16 v[20:23], v[144:147], v[214:217], v[20:23]
	v_mfma_f32_16x16x32_bf16 v[16:19], v[152:155], v[214:217], v[16:19]
	v_mfma_f32_16x16x32_bf16 v[4:7], v[144:147], v[222:225], v[4:7]
	v_mfma_f32_16x16x32_bf16 v[0:3], v[152:155], v[222:225], v[0:3]
	v_mfma_f32_16x16x32_bf16 v[48:51], v[156:159], v[198:201], v[32:35]
	v_mfma_f32_16x16x32_bf16 v[20:23], v[148:151], v[218:221], v[20:23]
	v_mfma_f32_16x16x32_bf16 v[16:19], v[156:159], v[218:221], v[16:19]
	v_mfma_f32_16x16x32_bf16 v[4:7], v[148:151], v[226:229], v[4:7]
	v_mfma_f32_16x16x32_bf16 v[0:3], v[156:159], v[226:229], v[0:3]
	s_setprio 0
	s_barrier
	s_add_i32 s56, s56, 2
	s_add_u32 s68, s68, 0x100
	s_addc_u32 s69, s69, 0
	s_add_u32 s14, s14, 0x100
	s_addc_u32 s15, s15, 0
	s_cmp_gt_u32 s56, 13
	s_cbranch_scc0 .LBB0_374
	s_and_b64 vcc, exec, s[18:19]
	s_cbranch_vccz .LBB0_377
	s_barrier

.LBB0_758:
	ds_read_b128 v[144:147], v153
	ds_read_b128 v[156:159], v153 offset:1024
	ds_read_b128 v[160:163], v153 offset:2048
	ds_read_b128 v[164:167], v153 offset:3072
	ds_read_b128 v[168:171], v154
	ds_read_b128 v[172:175], v154 offset:1024
	ds_read_b128 v[176:179], v154 offset:2048
	ds_read_b128 v[180:183], v154 offset:3072
	s_add_u32 s40, s38, 0xfffc0080
	s_addc_u32 s41, s39, -1
	s_cmp_eq_u32 s57, 12
	s_cselect_b32 s43, s21, s41
	s_cselect_b32 s42, s53, s40
	s_cselect_b32 s41, s19, s56
	s_cselect_b32 s40, s54, s55
	s_nop 0
	s_add_i32 m0, s27, 0xc000
	ds_read_b128 v[184:187], v155
	ds_read_b128 v[188:191], v155 offset:1024
	ds_read_b128 v[192:195], v155 offset:2048
	ds_read_b128 v[196:199], v155 offset:3072
	ds_read_b128 v[200:203], v155 offset:4096
	ds_read_b128 v[204:207], v155 offset:5120
	ds_read_b128 v[208:211], v155 offset:6144
	ds_read_b128 v[212:215], v155 offset:7168
	global_load_lds_dwordx4 v136, s[38:39]
	s_nop 0
	s_add_i32 m0, s27, 0xe000
	s_nop 0
	global_load_lds_dwordx4 v138, s[38:39]
	s_waitcnt vmcnt(8)
	s_waitcnt lgkmcnt(0)
	s_barrier
	s_setprio 1
	s_waitcnt lgkmcnt(0)
	v_mfma_f32_16x16x32_bf16 v[124:127], v[144:147], v[184:187], v[124:127]
	v_mfma_f32_16x16x32_bf16 v[120:123], v[160:163], v[184:187], v[120:123]
	v_mfma_f32_16x16x32_bf16 v[108:111], v[144:147], v[192:195], v[108:111]
	v_mfma_f32_16x16x32_bf16 v[104:107], v[160:163], v[192:195], v[104:107]
	v_mfma_f32_16x16x32_bf16 v[92:95], v[144:147], v[200:203], v[92:95]
	v_mfma_f32_16x16x32_bf16 v[88:91], v[160:163], v[200:203], v[88:91]
	v_mfma_f32_16x16x32_bf16 v[76:79], v[144:147], v[208:211], v[76:79]
	v_mfma_f32_16x16x32_bf16 v[72:75], v[160:163], v[208:211], v[72:75]
	v_mfma_f32_16x16x32_bf16 v[124:127], v[156:159], v[188:191], v[124:127]
	v_mfma_f32_16x16x32_bf16 v[120:123], v[164:167], v[188:191], v[120:123]
	v_mfma_f32_16x16x32_bf16 v[108:111], v[156:159], v[196:199], v[108:111]
	v_mfma_f32_16x16x32_bf16 v[104:107], v[164:167], v[196:199], v[104:107]
	v_mfma_f32_16x16x32_bf16 v[92:95], v[156:159], v[204:207], v[92:95]
	v_mfma_f32_16x16x32_bf16 v[88:91], v[164:167], v[204:207], v[88:91]
	v_mfma_f32_16x16x32_bf16 v[76:79], v[156:159], v[212:215], v[76:79]
	v_mfma_f32_16x16x32_bf16 v[72:75], v[164:167], v[212:215], v[72:75]
	s_setprio 0
	s_setprio 1
	v_mfma_f32_16x16x32_bf16 v[116:119], v[168:171], v[184:187], v[116:119]
	v_mfma_f32_16x16x32_bf16 v[112:115], v[176:179], v[184:187], v[112:115]
	v_mfma_f32_16x16x32_bf16 v[100:103], v[168:171], v[192:195], v[100:103]
	v_mfma_f32_16x16x32_bf16 v[96:99], v[176:179], v[192:195], v[96:99]
	v_mfma_f32_16x16x32_bf16 v[84:87], v[168:171], v[200:203], v[84:87]
	v_mfma_f32_16x16x32_bf16 v[80:83], v[176:179], v[200:203], v[80:83]
	v_mfma_f32_16x16x32_bf16 v[68:71], v[168:171], v[208:211], v[68:71]
	v_mfma_f32_16x16x32_bf16 v[64:67], v[176:179], v[208:211], v[64:67]
	v_mfma_f32_16x16x32_bf16 v[116:119], v[172:175], v[188:191], v[116:119]
	v_mfma_f32_16x16x32_bf16 v[112:115], v[180:183], v[188:191], v[112:115]
	v_mfma_f32_16x16x32_bf16 v[100:103], v[172:175], v[196:199], v[100:103]
	v_mfma_f32_16x16x32_bf16 v[96:99], v[180:183], v[196:199], v[96:99]
	v_mfma_f32_16x16x32_bf16 v[84:87], v[172:175], v[204:207], v[84:87]
	v_mfma_f32_16x16x32_bf16 v[80:83], v[180:183], v[204:207], v[80:83]
	v_mfma_f32_16x16x32_bf16 v[68:71], v[172:175], v[212:215], v[68:71]
	v_mfma_f32_16x16x32_bf16 v[64:67], v[180:183], v[212:215], v[64:67]
	s_setprio 0
	s_barrier
	s_add_i32 s58, s50, s33
	v_lshl_add_u64 v[148:149], s[40:41], 0, v[130:131]
	s_mov_b32 m0, s58
	ds_read_b128 v[184:187], v155 offset:16384
	ds_read_b128 v[188:191], v155 offset:17408
	ds_read_b128 v[192:195], v155 offset:18432
	ds_read_b128 v[196:199], v155 offset:19456
	ds_read_b128 v[200:203], v155 offset:20480
	ds_read_b128 v[204:207], v155 offset:21504
	ds_read_b128 v[208:211], v155 offset:22528
	ds_read_b128 v[212:215], v155 offset:23552
	global_load_lds_dwordx4 v[148:149], off
	s_add_i32 m0, s58, 0x2000
	s_add_u32 s58, s40, 0x40000
	v_lshl_add_u64 v[216:217], s[40:41], 0, v[134:135]
	s_addc_u32 s59, s41, 0
	s_add_i32 s60, s51, s33
	global_load_lds_dwordx4 v[216:217], off
	s_nop 0
	s_mov_b32 m0, s60
	v_lshl_add_u64 v[220:221], s[42:43], 0, v[132:133]
	global_load_lds_dwordx4 v130, s[58:59]
	s_nop 0
	s_add_i32 m0, s60, 0x2000
	s_nop 0
	global_load_lds_dwordx4 v134, s[58:59]
	v_lshl_add_u64 v[218:219], s[42:43], 0, v[128:129]
	s_mov_b32 m0, s27
	s_nop 0
	global_load_lds_dwordx4 v[218:219], off
	s_mov_b32 m0, s44
	s_nop 0
	global_load_lds_dwordx4 v[220:221], off
	s_waitcnt vmcnt(8)
	s_waitcnt lgkmcnt(0)
	s_barrier
	s_setprio 1
	s_waitcnt lgkmcnt(0)
	v_mfma_f32_16x16x32_bf16 v[60:63], v[144:147], v[184:187], v[60:63]
	v_mfma_f32_16x16x32_bf16 v[56:59], v[160:163], v[184:187], v[56:59]
	v_mfma_f32_16x16x32_bf16 v[44:47], v[144:147], v[192:195], v[44:47]
	v_mfma_f32_16x16x32_bf16 v[40:43], v[160:163], v[192:195], v[40:43]
	v_mfma_f32_16x16x32_bf16 v[28:31], v[144:147], v[200:203], v[28:31]
	v_mfma_f32_16x16x32_bf16 v[24:27], v[160:163], v[200:203], v[24:27]
	v_mfma_f32_16x16x32_bf16 v[12:15], v[144:147], v[208:211], v[12:15]
	v_mfma_f32_16x16x32_bf16 v[8:11], v[160:163], v[208:211], v[8:11]
	v_mfma_f32_16x16x32_bf16 v[60:63], v[156:159], v[188:191], v[60:63]
	v_mfma_f32_16x16x32_bf16 v[56:59], v[164:167], v[188:191], v[56:59]
	v_mfma_f32_16x16x32_bf16 v[44:47], v[156:159], v[196:199], v[44:47]
	v_mfma_f32_16x16x32_bf16 v[40:43], v[164:167], v[196:199], v[40:43]
	v_mfma_f32_16x16x32_bf16 v[28:31], v[156:159], v[204:207], v[28:31]
	v_mfma_f32_16x16x32_bf16 v[24:27], v[164:167], v[204:207], v[24:27]
	v_mfma_f32_16x16x32_bf16 v[12:15], v[156:159], v[212:215], v[12:15]
	v_mfma_f32_16x16x32_bf16 v[8:11], v[164:167], v[212:215], v[8:11]
	s_setprio 0
	s_setprio 1
	v_mfma_f32_16x16x32_bf16 v[52:55], v[168:171], v[184:187], v[52:55]
	v_mfma_f32_16x16x32_bf16 v[48:51], v[176:179], v[184:187], v[48:51]
	v_mfma_f32_16x16x32_bf16 v[36:39], v[168:171], v[192:195], v[36:39]
	v_mfma_f32_16x16x32_bf16 v[32:35], v[176:179], v[192:195], v[32:35]
	v_mfma_f32_16x16x32_bf16 v[20:23], v[168:171], v[200:203], v[20:23]
	v_mfma_f32_16x16x32_bf16 v[16:19], v[176:179], v[200:203], v[16:19]
	v_mfma_f32_16x16x32_bf16 v[4:7], v[168:171], v[208:211], v[4:7]
	v_mfma_f32_16x16x32_bf16 v[0:3], v[176:179], v[208:211], v[0:3]
	v_mfma_f32_16x16x32_bf16 v[52:55], v[172:175], v[188:191], v[52:55]
	v_mfma_f32_16x16x32_bf16 v[48:51], v[180:183], v[188:191], v[48:51]
	v_mfma_f32_16x16x32_bf16 v[36:39], v[172:175], v[196:199], v[36:39]
	v_mfma_f32_16x16x32_bf16 v[32:35], v[180:183], v[196:199], v[32:35]
	v_mfma_f32_16x16x32_bf16 v[20:23], v[172:175], v[204:207], v[20:23]
	v_mfma_f32_16x16x32_bf16 v[16:19], v[180:183], v[204:207], v[16:19]
	v_mfma_f32_16x16x32_bf16 v[4:7], v[172:175], v[212:215], v[4:7]
	v_mfma_f32_16x16x32_bf16 v[0:3], v[180:183], v[212:215], v[0:3]
	s_setprio 0
	s_barrier
	s_add_i32 s58, 0, 0x18000
	s_add_i32 s59, 0, 0x1c000
	v_add_u32_e32 v164, s58, v151
	v_add_u32_e32 v180, s59, v151
	ds_read_b128 v[144:147], v164
	ds_read_b128 v[156:159], v164 offset:1024
	ds_read_b128 v[160:163], v164 offset:2048
	ds_read_b128 v[164:167], v164 offset:3072
	ds_read_b128 v[168:171], v180
	ds_read_b128 v[172:175], v180 offset:1024
	ds_read_b128 v[176:179], v180 offset:2048
	ds_read_b128 v[180:183], v180 offset:3072
	s_add_u32 s42, s42, 0x40000
	s_addc_u32 s43, s43, 0
	s_mov_b32 m0, s45
	s_nop 0
	ds_read_b128 v[184:187], v155 offset:32768
	ds_read_b128 v[188:191], v155 offset:33792
	ds_read_b128 v[192:195], v155 offset:34816
	ds_read_b128 v[196:199], v155 offset:35840
	ds_read_b128 v[200:203], v155 offset:36864
	ds_read_b128 v[204:207], v155 offset:37888
	ds_read_b128 v[208:211], v155 offset:38912
	ds_read_b128 v[212:215], v155 offset:39936
	global_load_lds_dwordx4 v128, s[42:43]
	s_nop 0
	s_mov_b32 m0, s46
	s_nop 0
	global_load_lds_dwordx4 v132, s[42:43]
	s_waitcnt vmcnt(8)
	s_waitcnt lgkmcnt(0)
	s_barrier
	s_setprio 1
	s_waitcnt lgkmcnt(0)
	v_mfma_f32_16x16x32_bf16 v[124:127], v[144:147], v[184:187], v[124:127]
	v_mfma_f32_16x16x32_bf16 v[120:123], v[160:163], v[184:187], v[120:123]
	v_mfma_f32_16x16x32_bf16 v[108:111], v[144:147], v[192:195], v[108:111]
	v_mfma_f32_16x16x32_bf16 v[104:107], v[160:163], v[192:195], v[104:107]
	v_mfma_f32_16x16x32_bf16 v[92:95], v[144:147], v[200:203], v[92:95]
	v_mfma_f32_16x16x32_bf16 v[88:91], v[160:163], v[200:203], v[88:91]
	v_mfma_f32_16x16x32_bf16 v[76:79], v[144:147], v[208:211], v[76:79]
	v_mfma_f32_16x16x32_bf16 v[72:75], v[160:163], v[208:211], v[72:75]
	v_mfma_f32_16x16x32_bf16 v[124:127], v[156:159], v[188:191], v[124:127]
	v_mfma_f32_16x16x32_bf16 v[120:123], v[164:167], v[188:191], v[120:123]
	v_mfma_f32_16x16x32_bf16 v[108:111], v[156:159], v[196:199], v[108:111]
	v_mfma_f32_16x16x32_bf16 v[104:107], v[164:167], v[196:199], v[104:107]
	v_mfma_f32_16x16x32_bf16 v[92:95], v[156:159], v[204:207], v[92:95]
	v_mfma_f32_16x16x32_bf16 v[88:91], v[164:167], v[204:207], v[88:91]
	v_mfma_f32_16x16x32_bf16 v[76:79], v[156:159], v[212:215], v[76:79]
	v_mfma_f32_16x16x32_bf16 v[72:75], v[164:167], v[212:215], v[72:75]
	s_setprio 0
	s_setprio 1
	v_mfma_f32_16x16x32_bf16 v[116:119], v[168:171], v[184:187], v[116:119]
	v_mfma_f32_16x16x32_bf16 v[112:115], v[176:179], v[184:187], v[112:115]
	v_mfma_f32_16x16x32_bf16 v[100:103], v[168:171], v[192:195], v[100:103]
	v_mfma_f32_16x16x32_bf16 v[96:99], v[176:179], v[192:195], v[96:99]
	v_mfma_f32_16x16x32_bf16 v[84:87], v[168:171], v[200:203], v[84:87]
	v_mfma_f32_16x16x32_bf16 v[80:83], v[176:179], v[200:203], v[80:83]
	v_mfma_f32_16x16x32_bf16 v[68:71], v[168:171], v[208:211], v[68:71]
	v_mfma_f32_16x16x32_bf16 v[64:67], v[176:179], v[208:211], v[64:67]
	v_mfma_f32_16x16x32_bf16 v[116:119], v[172:175], v[188:191], v[116:119]
	v_mfma_f32_16x16x32_bf16 v[112:115], v[180:183], v[188:191], v[112:115]
	v_mfma_f32_16x16x32_bf16 v[100:103], v[172:175], v[196:199], v[100:103]
	v_mfma_f32_16x16x32_bf16 v[96:99], v[180:183], v[196:199], v[96:99]
	v_mfma_f32_16x16x32_bf16 v[84:87], v[172:175], v[204:207], v[84:87]
	v_mfma_f32_16x16x32_bf16 v[80:83], v[180:183], v[204:207], v[80:83]
	v_mfma_f32_16x16x32_bf16 v[68:71], v[172:175], v[212:215], v[68:71]
	v_mfma_f32_16x16x32_bf16 v[64:67], v[180:183], v[212:215], v[64:67]
	s_setprio 0
	s_barrier
	s_add_i32 s42, s58, s33
	v_lshl_add_u64 v[148:149], v[148:149], 0, s[6:7]
	s_mov_b32 m0, s42
	ds_read_b128 v[184:187], v155 offset:49152
	ds_read_b128 v[188:191], v155 offset:50176
	ds_read_b128 v[192:195], v155 offset:51200
	ds_read_b128 v[196:199], v155 offset:52224
	ds_read_b128 v[200:203], v155 offset:53248
	ds_read_b128 v[204:207], v155 offset:54272
	ds_read_b128 v[208:211], v155 offset:55296
	ds_read_b128 v[212:215], v155 offset:56320
	global_load_lds_dwordx4 v[148:149], off
	s_add_i32 m0, s42, 0x2000
	s_add_u32 s40, s40, 0x40080
	v_lshl_add_u64 v[148:149], v[216:217], 0, s[6:7]
	s_addc_u32 s41, s41, 0
	s_add_i32 s42, s59, s33
	global_load_lds_dwordx4 v[148:149], off
	s_nop 0
	s_mov_b32 m0, s42
	s_nop 0
	global_load_lds_dwordx4 v130, s[40:41]
	s_nop 0
	s_add_i32 m0, s42, 0x2000
	s_nop 0
	global_load_lds_dwordx4 v134, s[40:41]
	v_lshl_add_u64 v[148:149], v[218:219], 0, s[6:7]
	s_mov_b32 m0, s48
	s_nop 0
	global_load_lds_dwordx4 v[148:149], off
	v_lshl_add_u64 v[148:149], v[220:221], 0, s[6:7]
	s_mov_b32 m0, s49
	s_nop 0
	global_load_lds_dwordx4 v[148:149], off
	s_waitcnt vmcnt(8)
	s_waitcnt lgkmcnt(0)
	s_barrier
	s_setprio 1
	s_waitcnt lgkmcnt(0)
	v_mfma_f32_16x16x32_bf16 v[60:63], v[144:147], v[184:187], v[60:63]
	v_mfma_f32_16x16x32_bf16 v[56:59], v[160:163], v[184:187], v[56:59]
	v_mfma_f32_16x16x32_bf16 v[44:47], v[144:147], v[192:195], v[44:47]
	v_mfma_f32_16x16x32_bf16 v[40:43], v[160:163], v[192:195], v[40:43]
	v_mfma_f32_16x16x32_bf16 v[28:31], v[144:147], v[200:203], v[28:31]
	v_mfma_f32_16x16x32_bf16 v[24:27], v[160:163], v[200:203], v[24:27]
	v_mfma_f32_16x16x32_bf16 v[12:15], v[144:147], v[208:211], v[12:15]
	v_mfma_f32_16x16x32_bf16 v[8:11], v[160:163], v[208:211], v[8:11]
	v_mfma_f32_16x16x32_bf16 v[60:63], v[156:159], v[188:191], v[60:63]
	v_mfma_f32_16x16x32_bf16 v[56:59], v[164:167], v[188:191], v[56:59]
	v_mfma_f32_16x16x32_bf16 v[44:47], v[156:159], v[196:199], v[44:47]
	v_mfma_f32_16x16x32_bf16 v[40:43], v[164:167], v[196:199], v[40:43]
	v_mfma_f32_16x16x32_bf16 v[28:31], v[156:159], v[204:207], v[28:31]
	v_mfma_f32_16x16x32_bf16 v[24:27], v[164:167], v[204:207], v[24:27]
	v_mfma_f32_16x16x32_bf16 v[12:15], v[156:159], v[212:215], v[12:15]
	v_mfma_f32_16x16x32_bf16 v[8:11], v[164:167], v[212:215], v[8:11]
	s_setprio 0
	s_setprio 1
	v_mfma_f32_16x16x32_bf16 v[52:55], v[168:171], v[184:187], v[52:55]
	v_mfma_f32_16x16x32_bf16 v[48:51], v[176:179], v[184:187], v[48:51]
	v_mfma_f32_16x16x32_bf16 v[36:39], v[168:171], v[192:195], v[36:39]
	v_mfma_f32_16x16x32_bf16 v[32:35], v[176:179], v[192:195], v[32:35]
	v_mfma_f32_16x16x32_bf16 v[20:23], v[168:171], v[200:203], v[20:23]
	v_mfma_f32_16x16x32_bf16 v[16:19], v[176:179], v[200:203], v[16:19]
	v_mfma_f32_16x16x32_bf16 v[4:7], v[168:171], v[208:211], v[4:7]
	v_mfma_f32_16x16x32_bf16 v[0:3], v[176:179], v[208:211], v[0:3]
	v_mfma_f32_16x16x32_bf16 v[52:55], v[172:175], v[188:191], v[52:55]
	v_mfma_f32_16x16x32_bf16 v[48:51], v[180:183], v[188:191], v[48:51]
	v_mfma_f32_16x16x32_bf16 v[36:39], v[172:175], v[196:199], v[36:39]
	v_mfma_f32_16x16x32_bf16 v[32:35], v[180:183], v[196:199], v[32:35]
	v_mfma_f32_16x16x32_bf16 v[20:23], v[172:175], v[204:207], v[20:23]
	v_mfma_f32_16x16x32_bf16 v[16:19], v[180:183], v[204:207], v[16:19]
	v_mfma_f32_16x16x32_bf16 v[4:7], v[172:175], v[212:215], v[4:7]
	v_mfma_f32_16x16x32_bf16 v[0:3], v[180:183], v[212:215], v[0:3]
	s_setprio 0
	s_barrier
	s_add_i32 s57, s57, 2
	s_add_u32 s38, s38, 0x100
	s_addc_u32 s39, s39, 0
	s_add_u32 s55, s55, 0x100
	s_addc_u32 s56, s56, 0
	s_cmp_gt_u32 s57, 13
	s_cbranch_scc0 .LBB0_758
	s_and_b64 vcc, exec, s[8:9]
	s_cbranch_vccz .LBB0_761
	s_barrier
